# segment-edge lever: window/pass-2/pass-1 K-fragment LDS reads issued right behind the step barrier (scalar bookkeeping runs under the LDS latency)
# baseline (speedup 1.0000x reference)
.LBB0_708:
	v_add_u32_e32 v77, v58, v56
	ds_read_b128 v[160:163], v77
	ds_read_b128 v[164:167], v77 offset:64
	ds_read_b128 v[168:171], v77 offset:2304
	ds_read_b128 v[172:175], v77 offset:2368
	ds_read_b128 v[176:179], v77 offset:4608
	ds_read_b128 v[180:183], v77 offset:4672
	ds_read_b128 v[184:187], v77 offset:6912
	ds_read_b128 v[188:191], v77 offset:6976
	s_add_i32 s14, s2, 2
	s_cmp_lt_u32 s14, s12
	s_cselect_b64 s[10:11], -1, 0
	s_cmp_ge_u32 s14, s12
	s_cselect_b64 s[6:7], -1, 0
	s_and_b64 vcc, exec, s[6:7]
	s_cbranch_vccnz .LBB0_710
	v_add_co_u32_e32 v12, vcc, 0x2000, v50
	s_nop 1
	v_addc_co_u32_e32 v13, vcc, 0, v51, vcc
	global_load_dwordx4 v[12:15], v[12:13], off
.LBB0_710:
	v_cmp_ge_i32_e64 s[8:9], s13, v76
	s_mov_b64 s[4:5], -1
	s_and_b64 vcc, exec, s[8:9]
	v_add_u32_e32 v77, v58, v56
	s_cbranch_vccz .LBB0_732
	v_cvt_f32_i32_e32 v20, v75
	s_mov_b32 s4, 2.0
	s_mov_b32 s5, 0x40400000
	v_mul_f32_e64 v32, -v96, v20
	v_fma_f32 v21, -v96, v20, v60
	v_mov_b32_e32 v20, v32
	v_fmac_f32_e32 v20, 0, v60
	v_fma_f32 v22, v60, s4, v32
	v_fma_f32 v23, v61, s5, v32
	s_mov_b32 s4, 0x41800000
	s_mov_b32 s5, 0x41880000
	s_waitcnt lgkmcnt(7)
	v_mfma_f32_16x16x32_bf16 v[20:23], v[160:163], v[4:7], v[20:23]
	v_fma_f32 v26, v70, s90, v32
	v_fma_f32 v27, v71, s91, v32
	v_fma_f32 v24, v68, s4, v32
	v_fma_f32 v25, v69, s5, v32
	v_fma_f32 v30, v70, s92, v32
	v_fma_f32 v31, v71, s93, v32
	v_fma_f32 v28, v68, s34, v32
	v_fma_f32 v29, v69, s35, v32
	s_waitcnt lgkmcnt(6)
	v_mfma_f32_16x16x32_bf16 v[20:23], v[164:167], v[8:11], v[20:23]
	v_fma_f32 v34, v70, s22, v32
	v_fma_f32 v35, v71, s23, v32
	v_fma_f32 v33, v69, s73, v32
	v_fma_f32 v32, v68, s72, v32
	s_nop 4
	s_nop 0
	v_max3_f32 v78, v20, s36, v21
	s_waitcnt lgkmcnt(5)
	v_mfma_f32_16x16x32_bf16 v[24:27], v[168:171], v[4:7], v[24:27]
	v_max3_f32 v78, v78, v22, v23
	s_waitcnt lgkmcnt(4)
	v_mfma_f32_16x16x32_bf16 v[24:27], v[172:175], v[8:11], v[24:27]
	s_nop 6
	s_nop 0
	v_max3_f32 v78, v78, v24, v25
	s_waitcnt lgkmcnt(3)
	v_mfma_f32_16x16x32_bf16 v[28:31], v[176:179], v[4:7], v[28:31]
	v_max3_f32 v78, v78, v26, v27
	s_waitcnt lgkmcnt(2)
	v_mfma_f32_16x16x32_bf16 v[28:31], v[180:183], v[8:11], v[28:31]
	s_nop 6
	s_nop 0
	v_max3_f32 v78, v78, v28, v29
	s_waitcnt lgkmcnt(1)
	v_mfma_f32_16x16x32_bf16 v[32:35], v[184:187], v[4:7], v[32:35]
	v_max3_f32 v78, v78, v30, v31
	s_waitcnt lgkmcnt(0)
	v_mfma_f32_16x16x32_bf16 v[32:35], v[188:191], v[8:11], v[32:35]
	s_nop 7
	v_max3_f32 v78, v78, v32, v33
	v_max3_f32 v78, v78, v34, v35
	s_cbranch_execz .LBB0_733

.LBB0_720:
	v_add_f32_e32 v74, v74, v107
	s_andn2_b64 vcc, exec, s[4:5]
	s_mov_b64 s[4:5], -1
	s_waitcnt lgkmcnt(0)
	s_barrier
	s_cbranch_vccnz .LBB0_706
	v_add_u32_e32 v77, v57, v56
	ds_read_b128 v[160:163], v77
	ds_read_b128 v[164:167], v77 offset:64
	ds_read_b128 v[168:171], v77 offset:2304
	ds_read_b128 v[172:175], v77 offset:2368
	ds_read_b128 v[176:179], v77 offset:4608
	ds_read_b128 v[180:183], v77 offset:4672
	ds_read_b128 v[184:187], v77 offset:6912
	ds_read_b128 v[188:191], v77 offset:6976
	s_add_i32 s4, s2, 3
	s_cmp_ge_u32 s4, s12
	s_cbranch_scc1 .LBB0_723
	global_load_dwordx4 v[16:19], v[50:51], off
.LBB0_723:
	s_xor_b32 s2, s2, -2
	s_add_i32 s2, s2, s12
	s_lshl_b32 s15, s2, 10
	s_or_b32 s8, s15, 0x3f0
	s_cmp_ge_i32 s13, s8
	s_cselect_b64 s[8:9], -1, 0
	s_mov_b64 s[4:5], -1
	s_and_b64 vcc, exec, s[8:9]
	v_add_u32_e32 v77, v57, v56
	s_cbranch_vccz .LBB0_734
	v_subrev_u32_e32 v20, s15, v72
	v_cvt_f32_i32_e32 v20, v20
	s_mov_b32 s4, 2.0
	s_mov_b32 s5, 0x40400000
	v_mul_f32_e64 v32, -v96, v20
	v_fma_f32 v21, -v96, v20, v60
	v_mov_b32_e32 v20, v32
	v_fmac_f32_e32 v20, 0, v60
	v_fma_f32 v22, v60, s4, v32
	v_fma_f32 v23, v61, s5, v32
	s_mov_b32 s4, 0x41800000
	s_mov_b32 s5, 0x41880000
	s_waitcnt lgkmcnt(7)
	v_mfma_f32_16x16x32_bf16 v[20:23], v[160:163], v[4:7], v[20:23]
	v_fma_f32 v26, v70, s90, v32
	v_fma_f32 v27, v71, s91, v32
	v_fma_f32 v24, v68, s4, v32
	v_fma_f32 v25, v69, s5, v32
	v_fma_f32 v30, v70, s92, v32
	v_fma_f32 v31, v71, s93, v32
	s_waitcnt lgkmcnt(6)
	v_mfma_f32_16x16x32_bf16 v[20:23], v[164:167], v[8:11], v[20:23]
	v_fma_f32 v28, v68, s34, v32
	v_fma_f32 v29, v69, s35, v32
	v_fma_f32 v34, v70, s22, v32
	v_fma_f32 v35, v71, s23, v32
	s_waitcnt lgkmcnt(5)
	v_mfma_f32_16x16x32_bf16 v[24:27], v[168:171], v[4:7], v[24:27]
	v_fma_f32 v33, v69, s73, v32
	v_fma_f32 v32, v68, s72, v32
	s_nop 0
	s_nop 1
	v_max3_f32 v78, v20, s36, v21
	s_waitcnt lgkmcnt(4)
	v_mfma_f32_16x16x32_bf16 v[24:27], v[172:175], v[8:11], v[24:27]
	v_max3_f32 v78, v78, v22, v23
	s_waitcnt lgkmcnt(3)
	v_mfma_f32_16x16x32_bf16 v[28:31], v[176:179], v[4:7], v[28:31]
	s_nop 2
	s_nop 1
	v_max3_f32 v78, v78, v24, v25
	s_nop 0
	v_max3_f32 v78, v78, v26, v27
	s_waitcnt lgkmcnt(2)
	v_mfma_f32_16x16x32_bf16 v[28:31], v[180:183], v[8:11], v[28:31]
	s_nop 6
	s_nop 0
	v_max3_f32 v78, v78, v28, v29
	s_waitcnt lgkmcnt(1)
	v_mfma_f32_16x16x32_bf16 v[32:35], v[184:187], v[4:7], v[32:35]
	v_max3_f32 v78, v78, v30, v31
	s_waitcnt lgkmcnt(0)
	v_mfma_f32_16x16x32_bf16 v[32:35], v[188:191], v[8:11], v[32:35]
	s_nop 7
	v_max3_f32 v78, v78, v32, v33
	v_max3_f32 v78, v78, v34, v35
	s_cbranch_execz .LBB0_735

.LBB0_743:
	ds_read_b128 v[160:163], v118
	ds_read_b128 v[164:167], v118 offset:64
	ds_read_b128 v[168:171], v118 offset:2304
	ds_read_b128 v[172:175], v118 offset:2368
	ds_read_b128 v[176:179], v118 offset:4608
	ds_read_b128 v[180:183], v118 offset:4672
	ds_read_b128 v[184:187], v118 offset:6912
	ds_read_b128 v[188:191], v118 offset:6976
	s_add_i32 s20, s15, -1
	s_cmp_lt_u32 s20, s12
	s_cselect_b64 s[0:1], -1, 0
	s_cmp_ge_u32 s20, s12
	s_cbranch_scc1 .LBB0_745
	v_add_co_u32_e32 v28, vcc, 0xffffe000, v76
	s_add_i32 s88, s17, 0x80
	s_nop 0
	v_addc_co_u32_e32 v29, vcc, -1, v77, vcc
	v_lshl_add_u64 v[32:33], s[88:89], 1, v[72:73]
	global_load_dwordx4 v[28:31], v[28:29], off offset:-8
	s_nop 0
	global_load_dwordx4 v[32:35], v[32:33], off

.LBB0_747:
	v_cndmask_b32_e64 v78, 0, 1, s[4:5]
	s_mov_b64 s[6:7], -1
	v_cmp_ne_u32_e64 s[10:11], 1, v78
	s_andn2_b64 vcc, exec, s[4:5]
	s_waitcnt lgkmcnt(7)
	v_mfma_f32_16x16x32_bf16 v[52:55], v[160:163], v[4:7], v[52:55]
	s_waitcnt lgkmcnt(6)
	v_mfma_f32_16x16x32_bf16 v[52:55], v[164:167], v[8:11], v[52:55]
	ds_read_b128 v[196:199], v243
	ds_read_b128 v[200:203], v243 offset:64
	s_waitcnt lgkmcnt(7)
	v_mfma_f32_16x16x32_bf16 v[56:59], v[168:171], v[4:7], v[56:59]
	s_waitcnt lgkmcnt(6)
	v_mfma_f32_16x16x32_bf16 v[56:59], v[172:175], v[8:11], v[56:59]
	ds_read_b128 v[204:207], v243 offset:2304
	ds_read_b128 v[208:211], v243 offset:2368
	s_waitcnt lgkmcnt(7)
	v_mfma_f32_16x16x32_bf16 v[44:47], v[176:179], v[4:7], v[44:47]
	s_waitcnt lgkmcnt(6)
	v_mfma_f32_16x16x32_bf16 v[44:47], v[180:183], v[8:11], v[44:47]
	ds_read_b128 v[212:215], v243 offset:4608
	ds_read_b128 v[216:219], v243 offset:4672
	s_waitcnt lgkmcnt(7)
	v_mfma_f32_16x16x32_bf16 v[48:51], v[184:187], v[4:7], v[48:51]
	s_waitcnt lgkmcnt(6)
	v_mfma_f32_16x16x32_bf16 v[48:51], v[188:191], v[8:11], v[48:51]
	ds_read_b128 v[220:223], v243 offset:6912
	ds_read_b128 v[224:227], v243 offset:6976
	s_cbranch_vccnz .LBB0_749
	v_exp_f32_e32 v78, v52
	v_exp_f32_e32 v79, v56
	v_exp_f32_e32 v106, v53
	v_exp_f32_e32 v107, v57
	v_mul_f32_e32 v109, v74, v78
	v_mul_f32_e32 v110, v74, v79
	v_exp_f32_e32 v78, v54
	v_exp_f32_e32 v84, v58
	v_exp_f32_e32 v79, v55
	v_exp_f32_e32 v85, v59
	v_mul_f32_e32 v111, v74, v106
	v_mul_f32_e32 v121, v74, v107
	v_mul_f32_e64 v78, v74, v78
	v_mul_f32_e64 v79, v75, v79
	v_mul_f32_e64 v84, v74, v84
	v_mul_f32_e64 v85, v75, v85
	s_mov_b64 s[6:7], 0

.LBB0_761:
	s_andn2_b64 vcc, exec, s[4:5]
	s_waitcnt lgkmcnt(0)
	s_barrier
	s_cbranch_vccnz .LBB0_774
	ds_read_b128 v[160:163], v119
	ds_read_b128 v[164:167], v119 offset:64
	ds_read_b128 v[168:171], v119 offset:2304
	ds_read_b128 v[172:175], v119 offset:2368
	ds_read_b128 v[176:179], v119 offset:4608
	ds_read_b128 v[180:183], v119 offset:4672
	ds_read_b128 v[184:187], v119 offset:6912
	ds_read_b128 v[188:191], v119 offset:6976
	s_cmp_ge_u32 s15, s12
	s_cbranch_scc1 .LBB0_764
	s_add_i32 s88, s17, 0xc0
	v_lshl_add_u64 v[40:41], s[88:89], 1, v[72:73]
	global_load_dwordx4 v[36:39], v[76:77], off offset:-8
	s_nop 0
	global_load_dwordx4 v[40:43], v[40:41], off

.LBB0_766:
	v_cndmask_b32_e64 v78, 0, 1, s[4:5]
	s_mov_b64 s[6:7], -1
	v_cmp_ne_u32_e64 s[10:11], 1, v78
	s_andn2_b64 vcc, exec, s[4:5]
	s_waitcnt lgkmcnt(7)
	v_mfma_f32_16x16x32_bf16 v[52:55], v[160:163], v[4:7], v[52:55]
	s_waitcnt lgkmcnt(6)
	v_mfma_f32_16x16x32_bf16 v[52:55], v[164:167], v[8:11], v[52:55]
	ds_read_b128 v[196:199], v244
	ds_read_b128 v[200:203], v244 offset:64
	s_waitcnt lgkmcnt(7)
	v_mfma_f32_16x16x32_bf16 v[56:59], v[168:171], v[4:7], v[56:59]
	s_waitcnt lgkmcnt(6)
	v_mfma_f32_16x16x32_bf16 v[56:59], v[172:175], v[8:11], v[56:59]
	ds_read_b128 v[204:207], v244 offset:2304
	ds_read_b128 v[208:211], v244 offset:2368
	s_waitcnt lgkmcnt(7)
	v_mfma_f32_16x16x32_bf16 v[44:47], v[176:179], v[4:7], v[44:47]
	s_waitcnt lgkmcnt(6)
	v_mfma_f32_16x16x32_bf16 v[44:47], v[180:183], v[8:11], v[44:47]
	ds_read_b128 v[212:215], v244 offset:4608
	ds_read_b128 v[216:219], v244 offset:4672
	s_waitcnt lgkmcnt(7)
	v_mfma_f32_16x16x32_bf16 v[48:51], v[184:187], v[4:7], v[48:51]
	s_waitcnt lgkmcnt(6)
	v_mfma_f32_16x16x32_bf16 v[48:51], v[188:191], v[8:11], v[48:51]
	ds_read_b128 v[220:223], v244 offset:6912
	ds_read_b128 v[224:227], v244 offset:6976
	s_cbranch_vccnz .LBB0_768
	v_exp_f32_e32 v78, v52
	v_exp_f32_e32 v79, v56
	v_exp_f32_e32 v111, v53
	v_exp_f32_e32 v121, v57
	v_mul_f32_e32 v109, v74, v78
	v_mul_f32_e32 v110, v74, v79
	v_exp_f32_e32 v78, v54
	v_exp_f32_e32 v84, v58
	v_exp_f32_e32 v79, v55
	v_exp_f32_e32 v85, v59
	v_mul_f32_e32 v111, v74, v111
	v_mul_f32_e32 v121, v74, v121
	v_mul_f32_e64 v78, v74, v78
	v_mul_f32_e64 v79, v75, v79
	v_mul_f32_e64 v84, v74, v84
	v_mul_f32_e64 v85, v75, v85
	s_mov_b64 s[6:7], 0

.LBB0_1008:
	ds_read_b128 v[160:163], v118
	ds_read_b128 v[164:167], v118 offset:64
	ds_read_b128 v[168:171], v118 offset:2304
	ds_read_b128 v[172:175], v118 offset:2368
	ds_read_b128 v[176:179], v118 offset:4608
	ds_read_b128 v[180:183], v118 offset:4672
	ds_read_b128 v[184:187], v118 offset:6912
	ds_read_b128 v[188:191], v118 offset:6976
	s_add_i32 s16, s17, 2
	s_cmp_gt_i32 s16, s11
	s_cselect_b64 s[6:7], -1, 0
	s_cmp_le_i32 s16, s11
	s_cselect_b64 s[8:9], -1, 0
	s_and_b64 vcc, exec, s[6:7]
	s_cbranch_vccnz .LBB0_1010
	v_add_co_u32_e32 v2, vcc, 0x7c000, v110
	s_add_i32 s4, s0, 64
	s_nop 0
	v_addc_co_u32_e32 v3, vcc, 0, v111, vcc
	s_ashr_i32 s5, s4, 31
	global_load_dwordx4 v[44:47], v[2:3], off
	v_lshl_add_u64 v[2:3], s[4:5], 1, v[104:105]
	global_load_dwordx4 v[48:51], v[2:3], off

.LBB0_1016:
	s_andn2_b64 vcc, exec, s[4:5]
	s_waitcnt lgkmcnt(0)
	s_barrier
	s_cbranch_vccnz .LBB0_1028
	ds_read_b128 v[160:163], v119
	ds_read_b128 v[164:167], v119 offset:64
	ds_read_b128 v[168:171], v119 offset:2304
	ds_read_b128 v[172:175], v119 offset:2368
	ds_read_b128 v[176:179], v119 offset:4608
	ds_read_b128 v[180:183], v119 offset:4672
	ds_read_b128 v[184:187], v119 offset:6912
	ds_read_b128 v[188:191], v119 offset:6976
	s_cmp_gt_i32 s17, s12
	s_cbranch_scc1 .LBB0_1019
	s_ashr_i32 s1, s0, 31
	v_lshl_add_u64 v[56:57], s[0:1], 1, v[104:105]
	global_load_dwordx4 v[52:55], v[110:111], off
	s_nop 0
	global_load_dwordx4 v[56:59], v[56:57], off

.LBB0_1024:
	s_and_b64 vcc, exec, s[4:5]
	s_cbranch_vccz .LBB0_1014
	v_add_u32_e32 v0, s43, v120
	v_cvt_f32_i32_e32 v2, v0
	s_mov_b32 s4, 2.0
	s_mov_b32 s5, 0x40400000
	v_mul_f32_e64 v0, -v96, v2
	v_mov_b32_e32 v76, v0
	v_fma_f32 v77, -v96, v2, v96
	v_fmac_f32_e32 v76, 0, v96
	v_fma_f32 v78, v96, s4, v0
	v_fma_f32 v79, v97, s5, v0
	s_mov_b32 s4, 0x41800000
	s_mov_b32 s5, 0x41880000
	s_waitcnt lgkmcnt(7)
	v_mfma_f32_16x16x32_bf16 v[76:79], v[160:163], v[4:7], v[76:79]
	v_fma_f32 v82, v108, s90, v0
	v_fma_f32 v83, v109, s91, v0
	v_fma_f32 v80, v106, s4, v0
	v_fma_f32 v81, v107, s5, v0
	v_fma_f32 v130, v108, s92, v0
	v_fma_f32 v131, v109, s93, v0
	s_waitcnt lgkmcnt(6)
	v_mfma_f32_16x16x32_bf16 v[88:91], v[164:167], v[8:11], v[76:79]
	ds_read_b128 v[196:199], v243
	ds_read_b128 v[200:203], v243 offset:64
	s_nop 2
	v_fma_f32 v128, v106, s34, v0
	v_fma_f32 v129, v107, s35, v0
	v_fma_f32 v134, v108, s22, v0
	v_fma_f32 v135, v109, s23, v0
	s_waitcnt lgkmcnt(7)
	v_mfma_f32_16x16x32_bf16 v[76:79], v[168:171], v[4:7], v[80:83]
	s_nop 2
	v_fma_f32 v132, v106, s72, v0
	v_fma_f32 v133, v107, s73, v0
	v_max3_f32 v0, v88, s36, v89
	s_waitcnt lgkmcnt(6)
	v_mfma_f32_16x16x32_bf16 v[84:87], v[172:175], v[8:11], v[76:79]
	ds_read_b128 v[204:207], v243 offset:2304
	ds_read_b128 v[208:211], v243 offset:2368
	s_nop 2
	v_max3_f32 v0, v0, v90, v91
	s_waitcnt lgkmcnt(7)
	v_mfma_f32_16x16x32_bf16 v[76:79], v[176:179], v[4:7], v[128:131]
	s_nop 2
	v_max3_f32 v0, v0, v84, v85
	v_max3_f32 v0, v0, v86, v87
	s_waitcnt lgkmcnt(6)
	v_mfma_f32_16x16x32_bf16 v[76:79], v[180:183], v[8:11], v[76:79]
	ds_read_b128 v[212:215], v243 offset:4608
	ds_read_b128 v[216:219], v243 offset:4672
	s_waitcnt lgkmcnt(7)
	v_mfma_f32_16x16x32_bf16 v[80:83], v[184:187], v[4:7], v[132:135]
	s_nop 4
	v_max3_f32 v0, v0, v76, v77
	v_max3_f32 v0, v0, v78, v79
	s_waitcnt lgkmcnt(6)
	v_mfma_f32_16x16x32_bf16 v[80:83], v[188:191], v[8:11], v[80:83]
	ds_read_b128 v[220:223], v243 offset:6912
	ds_read_b128 v[224:227], v243 offset:6976
	s_nop 7
	v_max3_f32 v0, v0, v80, v81
	v_max3_f32 v0, v0, v82, v83
	v_cmp_gt_f32_e32 vcc, v0, v126
	s_cbranch_vccz .LBB0_1027
	ds_bpermute_b32 v2, v115, v0
	v_max_f32_e32 v0, v0, v0
	s_waitcnt lgkmcnt(0)
	v_max_f32_e32 v2, v2, v2
	v_max_f32_e32 v0, v0, v2
	ds_bpermute_b32 v2, v114, v0
	s_waitcnt lgkmcnt(0)
	v_max3_f32 v2, v126, v0, v2
	v_sub_f32_e32 v0, v126, v2
	v_exp_f32_e32 v0, v0
	v_mov_b32_e32 v126, v2
	v_mul_f32_e32 v127, v127, v0
	v_mul_f32_e64 v62, v62, v0
	v_mul_f32_e64 v63, v63, v0
	v_mul_f32_e64 v60, v60, v0
	v_mul_f32_e64 v61, v61, v0
	v_mul_f32_e64 v66, v66, v0
	v_mul_f32_e64 v67, v67, v0
	v_mul_f32_e64 v64, v64, v0
	v_mul_f32_e64 v65, v65, v0
	v_mul_f32_e64 v70, v70, v0
	v_mul_f32_e64 v71, v71, v0
	v_mul_f32_e64 v68, v68, v0
	v_mul_f32_e64 v69, v69, v0
	v_mul_f32_e64 v74, v74, v0
	v_mul_f32_e64 v75, v75, v0
	v_mul_f32_e64 v72, v72, v0
	v_mul_f32_e64 v73, v73, v0

.LBB0_1029:
	s_and_b64 vcc, exec, s[4:5]
	s_cbranch_vccz .LBB0_1023
	v_or_b32_e32 v3, s1, v98
	v_sub_u32_e32 v3, v103, v3
	v_cvt_f32_i32_e32 v3, v3
	s_mov_b32 s4, 2.0
	s_mov_b32 s5, 0x40400000
	v_mul_f32_e64 v68, -v96, v3
	v_fma_f32 v62, v96, s4, v68
	v_fma_f32 v63, v97, s5, v68
	s_mov_b32 s4, 0x41800000
	s_mov_b32 s5, 0x41880000
	v_mov_b32_e32 v60, v68
	v_fma_f32 v66, v108, s90, v68
	v_fma_f32 v67, v109, s91, v68
	v_fma_f32 v64, v106, s4, v68
	v_fma_f32 v65, v107, s5, v68
	v_fma_f32 v128, v108, s92, v68
	v_fma_f32 v129, v109, s93, v68
	v_fma_f32 v126, v106, s34, v68
	v_fma_f32 v127, v107, s35, v68
	v_fma_f32 v132, v108, s22, v68
	v_fma_f32 v133, v109, s23, v68
	v_fma_f32 v130, v106, s72, v68
	v_fma_f32 v131, v107, s73, v68
	v_fma_f32 v61, -v96, v3, v96
	v_fmac_f32_e32 v60, 0, v96
	s_nop 0
	s_waitcnt lgkmcnt(7)
	v_mfma_f32_16x16x32_bf16 v[60:63], v[160:163], v[4:7], v[60:63]
	s_waitcnt lgkmcnt(6)
	v_mfma_f32_16x16x32_bf16 v[72:75], v[164:167], v[8:11], v[60:63]
	ds_read_b128 v[196:199], v244
	ds_read_b128 v[200:203], v244 offset:64
	s_nop 4
	s_nop 1
	v_max3_f32 v3, v72, s36, v73
	s_waitcnt lgkmcnt(7)
	v_mfma_f32_16x16x32_bf16 v[60:63], v[168:171], v[4:7], v[64:67]
	s_nop 2
	v_max3_f32 v3, v3, v74, v75
	s_waitcnt lgkmcnt(6)
	v_mfma_f32_16x16x32_bf16 v[68:71], v[172:175], v[8:11], v[60:63]
	ds_read_b128 v[204:207], v244 offset:2304
	ds_read_b128 v[208:211], v244 offset:2368
	s_nop 2
	s_nop 2
	v_max3_f32 v3, v3, v68, v69
	s_waitcnt lgkmcnt(7)
	v_mfma_f32_16x16x32_bf16 v[60:63], v[176:179], v[4:7], v[126:129]
	s_nop 2
	v_max3_f32 v3, v3, v70, v71
	s_waitcnt lgkmcnt(6)
	v_mfma_f32_16x16x32_bf16 v[60:63], v[180:183], v[8:11], v[60:63]
	ds_read_b128 v[212:215], v244 offset:4608
	ds_read_b128 v[216:219], v244 offset:4672
	s_waitcnt lgkmcnt(7)
	v_mfma_f32_16x16x32_bf16 v[64:67], v[184:187], v[4:7], v[130:133]
	s_nop 4
	v_max3_f32 v3, v3, v60, v61
	v_max3_f32 v3, v3, v62, v63
	s_waitcnt lgkmcnt(6)
	v_mfma_f32_16x16x32_bf16 v[64:67], v[188:191], v[8:11], v[64:67]
	ds_read_b128 v[220:223], v244 offset:6912
	ds_read_b128 v[224:227], v244 offset:6976
	s_nop 7
	v_max3_f32 v3, v3, v64, v65
	v_max3_f32 v3, v3, v66, v67
	v_cmp_gt_f32_e32 vcc, v3, v0
	s_cbranch_vccz .LBB0_1032
	ds_bpermute_b32 v126, v115, v3
	v_max_f32_e32 v3, v3, v3
	s_waitcnt lgkmcnt(0)
	v_max_f32_e32 v126, v126, v126
	v_max_f32_e32 v3, v3, v126
	ds_bpermute_b32 v126, v114, v3
	s_waitcnt lgkmcnt(0)
	v_max3_f32 v3, v0, v3, v126
	v_sub_f32_e32 v0, v0, v3
	v_exp_f32_e32 v0, v0
	s_nop 0
	v_mul_f32_e32 v2, v2, v0
	v_mul_f32_e64 v78, v78, v0
	v_mul_f32_e64 v79, v79, v0
	v_mul_f32_e64 v76, v76, v0
	v_mul_f32_e64 v77, v77, v0
	v_mul_f32_e64 v82, v82, v0
	v_mul_f32_e64 v83, v83, v0
	v_mul_f32_e64 v80, v80, v0
	v_mul_f32_e64 v81, v81, v0
	v_mul_f32_e64 v86, v86, v0
	v_mul_f32_e64 v87, v87, v0
	v_mul_f32_e64 v84, v84, v0
	v_mul_f32_e64 v85, v85, v0
	v_mul_f32_e64 v90, v90, v0
	v_mul_f32_e64 v91, v91, v0
	v_mul_f32_e64 v88, v88, v0
	v_mul_f32_e64 v89, v89, v0
	v_mov_b32_e32 v0, v3
